# diff-attention QK: one counted lgkmcnt wait per MFMA (7..0) instead of lgkmcnt(0) before the first
# baseline (speedup 1.0000x reference)
; #define LAS __attribute__((address_space(3)))
; template <bool DIFF> ...
;     ...
;         const bool active = DIFF ? (64 * kt <= wrow) : true;
;         if (active) {
;             LAS const unsigned char* kb = DIFF ? lds + (it & 1) * DSTG : lds; LAS const unsigned char* vb = DIFF ? kb + 16384 : kb + KBY;
;             LAS const unsigned char* qa = lds + QOFF + (qr + l32) * QSTR + hi * 16;
;             f32x16 s0 = biasv, s1 = biasv;
;             LAS const unsigned char* ka = kb + l32 * KSTR + (DIFF ? c * 128 : 0) + hi * 16;
; #pragma unroll 1
;             for (int kq = 0; kq < NKS; kq += 4) {
;                 bf16x8 ka0[4], ka1[4], qq[4];
; #pragma unroll
;                 for (int j = 0; j < 4; ++j) {
;                     if (DIFF) { const int ko = 256 * l32 + 16 * (((c << 3) + 2 * j + hi) ^ (((l32 & 3) << 2) | ((l32 >> 2) & 3)));
;                         ka0[j] = *(LAS const bf16x8*)(kb + ko); ka1[j] = *(LAS const bf16x8*)(kb + 8192 + ko); }
;                     else { ka0[j] = *(LAS const bf16x8*)(ka + (kq + j) * 32); ka1[j] = *(LAS const bf16x8*)(ka + 32 * KSTR + (kq + j) * 32); }
;                     qq[j] = DIFF ? qf[DIFF ? j : 0] : *(LAS const bf16x8*)(qa + (kq + j) * 32); }
;                 __builtin_amdgcn_sched_barrier(0);
; #pragma unroll
;                 for (int j = 0; j < 4; ++j) { s0 = __builtin_amdgcn_mfma_f32_32x32x16_bf16(ka0[j], qq[j], s0, 0, 0, 0); s1 = __builtin_amdgcn_mfma_f32_32x32x16_bf16(ka1[j], qq[j], s1, 0, 0, 0); }
;             }
;             float c0 = 0.f, c1 = 0.f;
;             if (DIFF) {
;                 c0 = sl2 * (float)(64 * kt - wrow); c1 = sl2 * (float)(64 * kt + 32 - wrow);
;                 if (64 * kt + 64 > wrow) {
;                     asm volatile("" ::: "memory");
;                     const int irel = wrow + l32 - 64 * kt - hi * 4;
; #pragma unroll
;                     for (int r = 0; r < 16; ++r) { const int cr = (r >> 2) * 8 + (r & 3); if (cr > irel) s0[r] = -INFINITY; if (cr + 32 > irel) s1[r] = -INFINITY; }
;                 }
.LBB0_116:
	s_add_i32 s0, s25, s22
	s_add_i32 s1, s0, 64
	s_cmp_gt_u32 s1, s15
	s_cbranch_scc1 .LBB0_113
	s_and_b32 s1, s28, 0x8000
	s_add_i32 s23, s1, 0
	v_add_u32_e32 v86, s23, v200
	ds_read_b128 v[82:85], v86
	ds_read_b128 v[130:133], v86 offset:8192
	v_add_u32_e32 v86, s23, v201
	ds_read_b128 v[134:137], v86
	ds_read_b128 v[138:141], v86 offset:8192
	v_add_u32_e32 v86, s23, v202
	ds_read_b128 v[142:145], v86
	ds_read_b128 v[146:149], v86 offset:8192
	v_add_u32_e32 v86, s23, v203
	ds_read_b128 v[150:153], v86
	ds_read_b128 v[154:157], v86 offset:8192
	s_waitcnt lgkmcnt(7)
	v_mfma_f32_32x32x16_bf16 v[98:113], v[82:85], v[114:117], v[66:81]
	s_addk_i32 s0, 0x80
	s_cmp_le_u32 s0, s15
	s_waitcnt lgkmcnt(6)
	v_mfma_f32_32x32x16_bf16 v[82:97], v[130:133], v[114:117], v[66:81]
	s_waitcnt lgkmcnt(5)
	v_mfma_f32_32x32x16_bf16 v[98:113], v[134:137], v[118:121], v[98:113]
	s_waitcnt lgkmcnt(4)
	v_mfma_f32_32x32x16_bf16 v[82:97], v[138:141], v[118:121], v[82:97]
	s_waitcnt lgkmcnt(3)
	v_mfma_f32_32x32x16_bf16 v[98:113], v[142:145], v[122:125], v[98:113]
	s_waitcnt lgkmcnt(2)
	v_mfma_f32_32x32x16_bf16 v[82:97], v[146:149], v[122:125], v[82:97]
	s_waitcnt lgkmcnt(1)
	v_mfma_f32_32x32x16_bf16 v[98:113], v[150:153], v[126:129], v[98:113]
	s_waitcnt lgkmcnt(0)
	v_mfma_f32_32x32x16_bf16 v[82:97], v[154:157], v[126:129], v[82:97]
	s_cbranch_scc1 .LBB0_119
	v_cmp_gt_i32_e64 s[94:95], 26, v204
	s_mov_b64 s[2:3], s[96:97]
	v_cmp_gt_i32_e64 s[96:97], 27, v204
	v_cmp_gt_i32_e64 s[92:93], 25, v204
	s_and_b64 s[94:95], s[96:97], s[94:95]
	v_cmp_gt_i32_e64 s[90:91], 24, v204
	s_and_b64 s[92:93], s[94:95], s[92:93]
	v_cmp_gt_i32_e64 s[88:89], 19, v204
	s_and_b64 s[90:91], s[92:93], s[90:91]
	v_cmp_gt_i32_e64 s[86:87], 18, v204
	s_and_b64 s[88:89], s[90:91], s[88:89]
	v_cmp_gt_i32_e64 s[84:85], 17, v204
	s_and_b64 s[86:87], s[88:89], s[86:87]
	v_cmp_gt_i32_e64 s[82:83], 16, v204
	s_and_b64 s[84:85], s[86:87], s[84:85]
	v_cmp_gt_i32_e64 s[80:81], 11, v204
	s_and_b64 s[82:83], s[84:85], s[82:83]
	v_cmp_gt_i32_e64 s[78:79], 10, v204
	s_and_b64 s[80:81], s[82:83], s[80:81]
	v_cmp_gt_i32_e64 s[76:77], 9, v204
	s_and_b64 s[78:79], s[80:81], s[78:79]
	v_cmp_gt_i32_e64 s[74:75], 8, v204
	s_and_b64 s[76:77], s[78:79], s[76:77]
	v_cmp_gt_i32_e64 s[72:73], 3, v204
	s_and_b64 s[74:75], s[76:77], s[74:75]
	v_cmp_gt_i32_e64 s[70:71], 2, v204
	s_and_b64 s[72:73], s[74:75], s[72:73]
	v_cmp_gt_i32_e64 s[68:69], 1, v204
	s_and_b64 s[70:71], s[72:73], s[70:71]
	v_cmp_gt_i32_e64 s[66:67], 0, v204
	s_and_b64 s[68:69], s[70:71], s[68:69]
	s_and_b64 s[66:67], s[68:69], s[66:67]
	v_cmp_gt_i32_e64 s[62:63], 58, v204
	v_cndmask_b32_e64 v98, v98, v193, s[66:67]
	v_cmp_gt_i32_e64 s[66:67], 59, v204
	v_cmp_gt_i32_e64 s[60:61], 57, v204
	s_and_b64 s[62:63], s[66:67], s[62:63]
	v_cmp_gt_i32_e64 s[58:59], 56, v204
	s_and_b64 s[60:61], s[62:63], s[60:61]
	v_cmp_gt_i32_e64 s[56:57], 51, v204
	s_and_b64 s[58:59], s[60:61], s[58:59]
	v_cmp_gt_i32_e64 s[54:55], 50, v204
	s_and_b64 s[56:57], s[58:59], s[56:57]
	v_cmp_gt_i32_e64 s[52:53], 49, v204
	s_and_b64 s[54:55], s[56:57], s[54:55]
	v_cmp_gt_i32_e64 s[50:51], 48, v204
	s_and_b64 s[52:53], s[54:55], s[52:53]
	v_cmp_gt_i32_e64 s[48:49], 43, v204
	s_and_b64 s[50:51], s[52:53], s[50:51]
	v_cmp_gt_i32_e64 s[46:47], 42, v204
	s_and_b64 s[48:49], s[50:51], s[48:49]
	v_cmp_gt_i32_e64 s[42:43], 41, v204
	s_and_b64 s[46:47], s[48:49], s[46:47]
	v_cmp_gt_i32_e64 s[40:41], 40, v204
	s_and_b64 s[42:43], s[46:47], s[42:43]
	v_cmp_gt_i32_e64 s[38:39], 35, v204
	s_and_b64 s[40:41], s[42:43], s[40:41]
	v_cmp_gt_i32_e64 s[36:37], 34, v204
	s_and_b64 s[38:39], s[40:41], s[38:39]
	v_cmp_gt_i32_e64 s[0:1], 33, v204
	s_and_b64 s[36:37], s[38:39], s[36:37]
	v_cmp_gt_i32_e32 vcc, 32, v204
	s_and_b64 s[0:1], s[36:37], s[0:1]
	s_and_b64 vcc, s[0:1], vcc
	v_cndmask_b32_e64 v113, v113, v193, s[96:97]
	s_mov_b64 s[96:97], s[2:3]
	v_cndmask_b32_e64 v112, v112, v193, s[94:95]
	v_cndmask_b32_e64 v111, v111, v193, s[92:93]
	v_cndmask_b32_e64 v110, v110, v193, s[90:91]
	v_cndmask_b32_e64 v109, v109, v193, s[88:89]
	v_cndmask_b32_e64 v108, v108, v193, s[86:87]
	v_cndmask_b32_e64 v107, v107, v193, s[84:85]
	v_cndmask_b32_e64 v106, v106, v193, s[82:83]
	v_cndmask_b32_e64 v105, v105, v193, s[80:81]
	v_cndmask_b32_e64 v104, v104, v193, s[78:79]
	v_cndmask_b32_e64 v103, v103, v193, s[76:77]
	v_cndmask_b32_e64 v102, v102, v193, s[74:75]
	v_cndmask_b32_e64 v101, v101, v193, s[72:73]
	v_cndmask_b32_e64 v100, v100, v193, s[70:71]
	v_cndmask_b32_e64 v99, v99, v193, s[68:69]
	v_cndmask_b32_e64 v97, v97, v193, s[66:67]
	v_cndmask_b32_e64 v96, v96, v193, s[62:63]
	v_cndmask_b32_e64 v95, v95, v193, s[60:61]
	v_cndmask_b32_e64 v94, v94, v193, s[58:59]
	v_cndmask_b32_e64 v93, v93, v193, s[56:57]
	v_cndmask_b32_e64 v92, v92, v193, s[54:55]
	v_cndmask_b32_e64 v91, v91, v193, s[52:53]
	v_cndmask_b32_e64 v90, v90, v193, s[50:51]
	v_cndmask_b32_e64 v89, v89, v193, s[48:49]
	v_cndmask_b32_e64 v88, v88, v193, s[46:47]
	s_mov_b64 s[46:47], 0x1000
	v_cndmask_b32_e64 v87, v87, v193, s[42:43]
	s_mov_b64 s[42:43], 0xa110400
	v_cndmask_b32_e64 v86, v86, v193, s[40:41]
	v_cndmask_b32_e64 v85, v85, v193, s[38:39]
	v_cndmask_b32_e64 v84, v84, v193, s[36:37]
	v_cndmask_b32_e64 v83, v83, v193, s[0:1]
	v_cndmask_b32_e32 v82, v82, v193, vcc
